# v6 + hgrn workgroups skip gdnpre and run first 6 chain chunks during it (suspend/resume across the barrier)
# speedup vs baseline: 1.0140x; 1.0140x over previous
.Lhs_p3:
	s_movk_i32 s101, 6
	s_cmp_lt_u32 s62, 64
	s_cbranch_scc1 .Lhs_done
	s_sub_u32 s64, s62, 64
	s_movk_i32 s75, 0xc0
